# MLA loop: P.V k-step-major with exp/sum/pack of the next 16-key chunk issued between its MFMAs
# speedup vs baseline: 1.0145x; 1.0083x over previous
; __device__ __forceinline__ int crow(int r, int hi) { return (r & 3) + 8 * (r >> 2) + 4 * hi; }
; #define ATT_PK8(P, BASE, OUT) do { u32x4 w = {cvtpk(P[BASE + 0], P[BASE + 1]), cvtpk(P[BASE + 2], P[BASE + 3]), cvtpk(P[BASE + 4], P[BASE + 5]), cvtpk(P[BASE + 6], P[BASE + 7])}; \
;     OUT = *reinterpret_cast<bf16x8*>(&w); } while (0)
; template <bool RAW>
; __device__ __forceinline__ void softmax_tile(f32x16& p0, f32x16& p1, float Cs, float& m_reg, float& l_reg, float& alpha, bf16x8& pa0, bf16x8& pa1, bf16x8& pa2, bf16x8& pa3) {
;     ...
; #pragma unroll
;   for (int r = 0; r < 16; ++r) { p0[r] = __builtin_amdgcn_exp2f(RAW ? fmaf(p0[r], Cs, -mn) : p0[r] - mn); p1[r] = __builtin_amdgcn_exp2f(RAW ? fmaf(p1[r], Cs, -mn) : p1[r] - mn); }
;   f32x2 ps2 = {0.f, 0.f};
; #pragma unroll
;   for (int r = 0; r < 16; r += 2) { ps2 += (f32x2){p0[r], p0[r + 1]}; ps2 += (f32x2){p1[r], p1[r + 1]}; }
;   l_reg = l_reg * alpha + (ps2[0] + ps2[1]);
;     ...
;   ATT_PK8(p0, 0, pa0); ATT_PK8(p0, 8, pa1); ATT_PK8(p1, 0, pa2); ATT_PK8(p1, 8, pa3);
; template <int MODE>
; __device__ __forceinline__ void attn_unit(unsigned char* ws_, const float* rpb, const float* sink, int l, int h, int qb, int kvq, unsigned char* lds_g) {
;     ...
;       if (__any(alpha < 1.f)) { if (hi == 0) al_l[r32] = alpha; asm volatile("s_waitcnt lgkmcnt(0)" ::: "memory");
; #pragma unroll
;         for (int r = 0; r < 16; ++r) { const float av = al_l[crow(r, hi)];
; #pragma unroll
;           for (int d = 0; d < 4; ++d) o[d][r] *= av; }
;         asm volatile("s_waitcnt lgkmcnt(0)" ::: "memory"); }
.LBB0_868:
	v_cmp_gt_f32_e32 vcc, 1.0, v203
	s_cbranch_vccz .Lmla_nors
	s_and_saveexec_b64 s[8:9], s[4:5]
	ds_write_b32 v182, v203 offset:128
	s_or_b64 exec, exec, s[8:9]
	s_waitcnt lgkmcnt(0)
	v_add_u32_e32 v230, v178, v0
	ds_read_b128 v[204:207], v230 offset:224
	ds_read_b128 v[208:211], v230 offset:192
	ds_read_b128 v[212:215], v230 offset:160
	ds_read_b128 v[236:239], v230 offset:128
	s_waitcnt lgkmcnt(0)
	s_waitcnt lgkmcnt(0)
	v_pk_mul_f32 v[14:15], v[14:15], v[204:205]
	v_pk_mul_f32 v[10:11], v[10:11], v[208:209]
	v_pk_mul_f32 v[6:7], v[6:7], v[212:213]
	v_pk_mul_f32 v[16:17], v[16:17], v[206:207]
	v_pk_mul_f32 v[12:13], v[12:13], v[210:211]
	v_pk_mul_f32 v[8:9], v[8:9], v[214:215]
	v_pk_mul_f32 v[4:5], v[4:5], v[238:239]
	v_pk_mul_f32 v[2:3], v[2:3], v[236:237]
	v_pk_mul_f32 v[62:63], v[62:63], v[204:205]
	v_pk_mul_f32 v[58:59], v[58:59], v[208:209]
	v_pk_mul_f32 v[54:55], v[54:55], v[212:213]
	v_pk_mul_f32 v[64:65], v[64:65], v[206:207]
	v_pk_mul_f32 v[60:61], v[60:61], v[210:211]
	v_pk_mul_f32 v[56:57], v[56:57], v[214:215]
	v_pk_mul_f32 v[52:53], v[52:53], v[238:239]
	v_pk_mul_f32 v[50:51], v[50:51], v[236:237]
	v_pk_mul_f32 v[46:47], v[46:47], v[204:205]
	v_pk_mul_f32 v[42:43], v[42:43], v[208:209]
	v_pk_mul_f32 v[38:39], v[38:39], v[212:213]
	v_pk_mul_f32 v[48:49], v[48:49], v[206:207]
	v_pk_mul_f32 v[44:45], v[44:45], v[210:211]
	v_pk_mul_f32 v[40:41], v[40:41], v[214:215]
	v_pk_mul_f32 v[36:37], v[36:37], v[238:239]
	v_pk_mul_f32 v[34:35], v[34:35], v[236:237]
	v_pk_mul_f32 v[30:31], v[30:31], v[204:205]
	v_pk_mul_f32 v[26:27], v[26:27], v[208:209]
	v_pk_mul_f32 v[22:23], v[22:23], v[212:213]
	v_pk_mul_f32 v[32:33], v[32:33], v[206:207]
	v_pk_mul_f32 v[28:29], v[28:29], v[210:211]
	v_pk_mul_f32 v[24:25], v[24:25], v[214:215]
	v_pk_mul_f32 v[20:21], v[20:21], v[238:239]
	v_pk_mul_f32 v[18:19], v[18:19], v[236:237]
; #define ATT_SBAR() __builtin_amdgcn_sched_barrier(0)
; template <int D0> __device__ __forceinline__ void pv_read(VFrag& f, int vb) {
;   f.l0 = tr_read<v_rd_off(D0, 0, 0)>(vb); f.h0 = tr_read<v_rd_off(D0, 0, 1)>(vb); f.l1 = tr_read<v_rd_off(D0, 1, 0)>(vb); f.h1 = tr_read<v_rd_off(D0, 1, 1)>(vb);
;   f.l2 = tr_read<v_rd_off(D0, 2, 0)>(vb); f.h2 = tr_read<v_rd_off(D0, 2, 1)>(vb); f.l3 = tr_read<v_rd_off(D0, 3, 0)>(vb); f.h3 = tr_read<v_rd_off(D0, 3, 1)>(vb);
; }
; __device__ __forceinline__ void pv_mma(f32x16& od, const VFrag& f, bf16x8 pa0, bf16x8 pa1, bf16x8 pa2, bf16x8 pa3) {
;     ...
;   od = __builtin_amdgcn_mfma_f32_32x32x16_bf16(pa0, ATT_PK(f.l0, f.h0), od, 0, 0, 0);
;   od = __builtin_amdgcn_mfma_f32_32x32x16_bf16(pa1, ATT_PK(f.l1, f.h1), od, 0, 0, 0);
;   od = __builtin_amdgcn_mfma_f32_32x32x16_bf16(pa2, ATT_PK(f.l2, f.h2), od, 0, 0, 0);
;   od = __builtin_amdgcn_mfma_f32_32x32x16_bf16(pa3, ATT_PK(f.l3, f.h3), od, 0, 0, 0);
;     ...
; }
; __device__ __forceinline__ void pv_d0(f32x16* o, int vb, bf16x8 pa0, bf16x8 pa1, bf16x8 pa2, bf16x8 pa3) {
;   VFrag fa, fb;
;   pv_read<0>(fa, vb); pv_read<1>(fb, vb);
;   asm volatile("s_waitcnt lgkmcnt(8)" ::: "memory"); ATT_SBAR(); pv_mma(o[0], fa, pa0, pa1, pa2, pa3); ATT_SBAR();
;   pv_read<2>(fa, vb);
;   asm volatile("s_waitcnt lgkmcnt(8)" ::: "memory"); ATT_SBAR(); pv_mma(o[1], fb, pa0, pa1, pa2, pa3); ATT_SBAR();
;   pv_read<3>(fb, vb);
;   asm volatile("s_waitcnt lgkmcnt(8)" ::: "memory"); ATT_SBAR(); pv_mma(o[2], fa, pa0, pa1, pa2, pa3); ATT_SBAR();
;   asm volatile("s_waitcnt lgkmcnt(0)" ::: "memory"); ATT_SBAR(); pv_mma(o[3], fb, pa0, pa1, pa2, pa3);
; template <bool RAW>
; __device__ __forceinline__ void softmax_tile(f32x16& p0, f32x16& p1, float Cs, float& m_reg, float& l_reg, float& alpha, bf16x8& pa0, bf16x8& pa1, bf16x8& pa2, bf16x8& pa3) {
;     ...
; #pragma unroll
;   for (int r = 0; r < 16; ++r) { p0[r] = __builtin_amdgcn_exp2f(RAW ? fmaf(p0[r], Cs, -mn) : p0[r] - mn); p1[r] = __builtin_amdgcn_exp2f(RAW ? fmaf(p1[r], Cs, -mn) : p1[r] - mn); }
;   f32x2 ps2 = {0.f, 0.f};
; #pragma unroll
;   for (int r = 0; r < 16; r += 2) { ps2 += (f32x2){p0[r], p0[r + 1]}; ps2 += (f32x2){p1[r], p1[r + 1]}; }
;   l_reg = l_reg * alpha + (ps2[0] + ps2[1]);
;     ...
;   ATT_PK8(p0, 0, pa0); ATT_PK8(p0, 8, pa1); ATT_PK8(p1, 0, pa2); ATT_PK8(p1, 8, pa3);
.Lmla_nors:
	v_lshl_add_u32 v230, s10, 14, v200
	ds_read_b64_tr_b16 v[160:161], v230 offset:0
	ds_read_b64_tr_b16 v[162:163], v230 offset:2048
	ds_read_b64_tr_b16 v[164:165], v230 offset:512
	ds_read_b64_tr_b16 v[166:167], v230 offset:2560
	ds_read_b64_tr_b16 v[168:169], v230 offset:1024
	ds_read_b64_tr_b16 v[170:171], v230 offset:3072
	ds_read_b64_tr_b16 v[172:173], v230 offset:1536
	ds_read_b64_tr_b16 v[174:175], v230 offset:3584
	v_mov_b32_e32 v252, 0
	v_mov_b32_e32 v253, 0
	v_fma_f32 v82, v82, s56, -v148
	v_exp_f32_e32 v82, v82
	v_fma_f32 v83, v83, s56, -v148
	v_exp_f32_e32 v83, v83
	v_fma_f32 v84, v84, s56, -v148
	v_exp_f32_e32 v84, v84
	v_fma_f32 v85, v85, s56, -v148
	v_exp_f32_e32 v85, v85
	v_fma_f32 v86, v86, s56, -v148
	v_exp_f32_e32 v86, v86
	v_fma_f32 v87, v87, s56, -v148
	v_exp_f32_e32 v87, v87
	v_fma_f32 v88, v88, s56, -v148
	v_exp_f32_e32 v88, v88
	v_fma_f32 v89, v89, s56, -v148
	v_exp_f32_e32 v89, v89
	v_add_f32_e32 v252, v252, v82
	v_add_f32_e32 v253, v253, v83
	v_add_f32_e32 v252, v252, v84
	v_add_f32_e32 v253, v253, v85
	v_cvt_pk_bf16_f32 v204, v82, v83
	v_cvt_pk_bf16_f32 v205, v84, v85
	v_add_f32_e32 v252, v252, v86
	v_add_f32_e32 v253, v253, v87
	v_add_f32_e32 v252, v252, v88
	v_add_f32_e32 v253, v253, v89
	v_cvt_pk_bf16_f32 v206, v86, v87
	v_cvt_pk_bf16_f32 v207, v88, v89
	ds_read_b64_tr_b16 v[240:241], v230 offset:4096
	ds_read_b64_tr_b16 v[242:243], v230 offset:6144
	ds_read_b64_tr_b16 v[244:245], v230 offset:4608
	ds_read_b64_tr_b16 v[246:247], v230 offset:6656
	ds_read_b64_tr_b16 v[248:249], v230 offset:5120
	ds_read_b64_tr_b16 v[250:251], v230 offset:7168
	ds_read_b64_tr_b16 v[84:85], v230 offset:5632
	ds_read_b64_tr_b16 v[86:87], v230 offset:7680
	s_waitcnt lgkmcnt(8)
	v_mfma_f32_32x32x16_bf16 v[2:17], v[204:207], v[160:163], v[2:17]
	v_fma_f32 v90, v90, s56, -v148
	v_exp_f32_e32 v90, v90
	v_fma_f32 v91, v91, s56, -v148
	v_exp_f32_e32 v91, v91
	v_fma_f32 v92, v92, s56, -v148
	v_exp_f32_e32 v92, v92
	v_fma_f32 v93, v93, s56, -v148
	v_exp_f32_e32 v93, v93
	v_mfma_f32_32x32x16_bf16 v[50:65], v[204:207], v[164:167], v[50:65]
	v_fma_f32 v94, v94, s56, -v148
	v_exp_f32_e32 v94, v94
	v_fma_f32 v95, v95, s56, -v148
	v_exp_f32_e32 v95, v95
	v_fma_f32 v96, v96, s56, -v148
	v_exp_f32_e32 v96, v96
	v_fma_f32 v97, v97, s56, -v148
	v_exp_f32_e32 v97, v97
	v_mfma_f32_32x32x16_bf16 v[34:49], v[204:207], v[168:171], v[34:49]
	v_add_f32_e32 v252, v252, v90
	v_add_f32_e32 v253, v253, v91
	v_add_f32_e32 v252, v252, v92
	v_add_f32_e32 v253, v253, v93
	v_cvt_pk_bf16_f32 v208, v90, v91
	v_cvt_pk_bf16_f32 v209, v92, v93
	v_add_f32_e32 v252, v252, v94
	v_mfma_f32_32x32x16_bf16 v[18:33], v[204:207], v[172:175], v[18:33]
	v_add_f32_e32 v253, v253, v95
	v_add_f32_e32 v252, v252, v96
	v_add_f32_e32 v253, v253, v97
	v_cvt_pk_bf16_f32 v210, v94, v95
	v_cvt_pk_bf16_f32 v211, v96, v97
	ds_read_b64_tr_b16 v[160:161], v230 offset:8192
	ds_read_b64_tr_b16 v[162:163], v230 offset:10240
	ds_read_b64_tr_b16 v[164:165], v230 offset:8704
	ds_read_b64_tr_b16 v[166:167], v230 offset:10752
	ds_read_b64_tr_b16 v[168:169], v230 offset:9216
	ds_read_b64_tr_b16 v[170:171], v230 offset:11264
	ds_read_b64_tr_b16 v[172:173], v230 offset:9728
	ds_read_b64_tr_b16 v[174:175], v230 offset:11776
	s_waitcnt lgkmcnt(8)
	v_mfma_f32_32x32x16_bf16 v[2:17], v[208:211], v[240:243], v[2:17]
	v_fma_f32 v66, v66, s56, -v148
	v_exp_f32_e32 v66, v66
	v_fma_f32 v67, v67, s56, -v148
	v_exp_f32_e32 v67, v67
	v_fma_f32 v68, v68, s56, -v148
	v_exp_f32_e32 v68, v68
	v_fma_f32 v69, v69, s56, -v148
	v_exp_f32_e32 v69, v69
	v_mfma_f32_32x32x16_bf16 v[50:65], v[208:211], v[244:247], v[50:65]
	v_fma_f32 v70, v70, s56, -v148
	v_exp_f32_e32 v70, v70
	v_fma_f32 v71, v71, s56, -v148
	v_exp_f32_e32 v71, v71
	v_fma_f32 v72, v72, s56, -v148
	v_exp_f32_e32 v72, v72
	v_fma_f32 v73, v73, s56, -v148
	v_exp_f32_e32 v73, v73
	v_mfma_f32_32x32x16_bf16 v[34:49], v[208:211], v[248:251], v[34:49]
	v_add_f32_e32 v252, v252, v66
	v_add_f32_e32 v253, v253, v67
	v_add_f32_e32 v252, v252, v68
	v_add_f32_e32 v253, v253, v69
	v_cvt_pk_bf16_f32 v212, v66, v67
	v_cvt_pk_bf16_f32 v213, v68, v69
	v_add_f32_e32 v252, v252, v70
	v_mfma_f32_32x32x16_bf16 v[18:33], v[208:211], v[84:87], v[18:33]
	v_add_f32_e32 v253, v253, v71
	v_add_f32_e32 v252, v252, v72
	v_add_f32_e32 v253, v253, v73
	v_cvt_pk_bf16_f32 v214, v70, v71
	v_cvt_pk_bf16_f32 v215, v72, v73
	ds_read_b64_tr_b16 v[240:241], v230 offset:12288
	ds_read_b64_tr_b16 v[242:243], v230 offset:14336
	ds_read_b64_tr_b16 v[244:245], v230 offset:12800
	ds_read_b64_tr_b16 v[246:247], v230 offset:14848
	ds_read_b64_tr_b16 v[248:249], v230 offset:13312
	ds_read_b64_tr_b16 v[250:251], v230 offset:15360
	ds_read_b64_tr_b16 v[84:85], v230 offset:13824
	ds_read_b64_tr_b16 v[86:87], v230 offset:15872
	s_waitcnt lgkmcnt(8)
	v_mfma_f32_32x32x16_bf16 v[2:17], v[212:215], v[160:163], v[2:17]
	v_fma_f32 v74, v74, s56, -v148
	v_exp_f32_e32 v74, v74
	v_fma_f32 v75, v75, s56, -v148
	v_exp_f32_e32 v75, v75
	v_fma_f32 v76, v76, s56, -v148
	v_exp_f32_e32 v76, v76
	v_fma_f32 v77, v77, s56, -v148
	v_exp_f32_e32 v77, v77
	v_mfma_f32_32x32x16_bf16 v[50:65], v[212:215], v[164:167], v[50:65]
	v_fma_f32 v78, v78, s56, -v148
	v_exp_f32_e32 v78, v78
	v_fma_f32 v79, v79, s56, -v148
	v_exp_f32_e32 v79, v79
	v_fma_f32 v80, v80, s56, -v148
	v_exp_f32_e32 v80, v80
	v_fma_f32 v81, v81, s56, -v148
	v_exp_f32_e32 v81, v81
	v_mfma_f32_32x32x16_bf16 v[34:49], v[212:215], v[168:171], v[34:49]
	v_add_f32_e32 v252, v252, v74
	v_add_f32_e32 v253, v253, v75
	v_add_f32_e32 v252, v252, v76
	v_add_f32_e32 v253, v253, v77
	v_cvt_pk_bf16_f32 v236, v74, v75
	v_cvt_pk_bf16_f32 v237, v76, v77
	v_add_f32_e32 v252, v252, v78
	v_mfma_f32_32x32x16_bf16 v[18:33], v[212:215], v[172:175], v[18:33]
	v_add_f32_e32 v253, v253, v79
	v_add_f32_e32 v252, v252, v80
	v_add_f32_e32 v253, v253, v81
	v_cvt_pk_bf16_f32 v238, v78, v79
	v_cvt_pk_bf16_f32 v239, v80, v81
	s_waitcnt lgkmcnt(0)
	s_nop 0
	v_mfma_f32_32x32x16_bf16 v[2:17], v[236:239], v[240:243], v[2:17]
	v_add_f32_e32 v252, v252, v253
	v_mfma_f32_32x32x16_bf16 v[50:65], v[236:239], v[244:247], v[50:65]
	v_fmac_f32_e32 v252, v202, v203
	v_mfma_f32_32x32x16_bf16 v[34:49], v[236:239], v[248:251], v[34:49]
	v_mov_b32_e32 v202, v252
	v_mfma_f32_32x32x16_bf16 v[18:33], v[236:239], v[84:87], v[18:33]
